# stack of small instruction-level trims on the best version: merge hook vmcnt ladder, D epilogue batched gain loads and 16-byte stores, QK-norm branch-free column select, B latent tiles batched bias re
# speedup vs baseline: 1.0063x; 1.0027x over previous
; #define ISSUE(t, KR, VR) do { const GAS bf16_t* tb_ = (const GAS bf16_t*)Z + (size_t)TILE_ROW(t) * ZW; \
;         KR[0] = *(const GAS u32x4*)(tb_ + koff); KR[1] = *(const GAS u32x4*)(tb_ + koff + 64); \
;         VR[0] = *(const GAS u32x4*)(tb_ + voff); VR[1] = *(const GAS u32x4*)(tb_ + voff + ZW); } while (0)
; template <int MODE>
; DI void attn_unit(const Ctx& C, const bf16_t* __restrict__ Z, bf16_t* __restrict__ Y, int b, int qsel, int hsel, bool ctxq,
;                   const float* sinkp, const float* rpb_h, float lam, float post_scale, const float* subln, const float mref) {
;     ...
;     for (int t = 0; t < nt; ++t) {
;         if (t + 1 < nt) {
;             if ((t + 1) & 1) { WRITE(1, kB, vB); if (t + 3 < nt) ISSUE(t + 3, kB, vB); }
;             else { WRITE(0, kA, vA); if (t + 3 < nt) ISSUE(t + 3, kA, vA); }
.LBB0_454:
	s_add_i32 s70, s62, -1
	s_cmp_ge_i32 s62, s64
	s_cbranch_scc1 .LBB0_463
	s_bitcmp0_b32 s70, 0
	s_cbranch_scc1 .Lbl_even
	s_cmp_le_i32 s62, s63
	s_cbranch_scc1 .Lbl_odd_w4
	s_waitcnt vmcnt(0)
	s_branch .Lbl_odd_go

; #define ISSUE(t, KR, VR) do { const GAS bf16_t* tb_ = (const GAS bf16_t*)Z + (size_t)TILE_ROW(t) * ZW; \
;         KR[0] = *(const GAS u32x4*)(tb_ + koff); KR[1] = *(const GAS u32x4*)(tb_ + koff + 64); \
;         VR[0] = *(const GAS u32x4*)(tb_ + voff); VR[1] = *(const GAS u32x4*)(tb_ + voff + ZW); } while (0)
; template <int MODE>
; DI void attn_unit(const Ctx& C, const bf16_t* __restrict__ Z, bf16_t* __restrict__ Y, int b, int qsel, int hsel, bool ctxq,
;                   const float* sinkp, const float* rpb_h, float lam, float post_scale, const float* subln, const float mref) {
;     ...
;             if ((t + 1) & 1) { WRITE(1, kB, vB); if (t + 3 < nt) ISSUE(t + 3, kB, vB); }
;             else { WRITE(0, kA, vA); if (t + 3 < nt) ISSUE(t + 3, kA, vA); }
.Lbl_odd_go:
	ds_write_b128 v117, v[36:39]
	ds_write_b128 v117, v[40:43] offset:9216
	ds_write_b16 v116, v52 offset:18432
	ds_write_b16_d16_hi v116, v52 offset:18704
	ds_write_b16 v116, v53 offset:18976
	ds_write_b16_d16_hi v116, v53 offset:19248
	ds_write_b16 v116, v54 offset:19520
	ds_write_b16_d16_hi v116, v54 offset:19792
	ds_write_b16 v116, v55 offset:20064
	ds_write_b16_d16_hi v116, v55 offset:20336
	ds_write_b16 v116, v56 offset:18560
	ds_write_b16_d16_hi v116, v56 offset:18832
	ds_write_b16 v116, v57 offset:19104
	ds_write_b16_d16_hi v116, v57 offset:19376
	ds_write_b16 v116, v58 offset:19648
	ds_write_b16_d16_hi v116, v58 offset:19920
	ds_write_b16 v116, v59 offset:20192
	ds_write_b16_d16_hi v116, v59 offset:20464
	s_cmp_lt_i32 s62, s63
	s_cbranch_scc0 .LBB0_463
	s_mul_i32 s26, s66, 0x2200
	s_mul_hi_i32 s27, s66, 0x2200
	s_add_u32 s26, s8, s26
	s_addc_u32 s27, s9, s27
	v_lshl_add_u64 v[84:85], v[0:1], 1, s[26:27]
	v_add_co_u32_e32 v86, vcc, 0x88000, v84
	v_lshl_add_u64 v[92:93], v[102:103], 1, s[26:27]
	s_nop 0
	v_addc_co_u32_e32 v87, vcc, 0, v85, vcc
	v_add_co_u32_e32 v96, vcc, 0x88000, v92
	global_load_dwordx4 v[36:39], v[84:85], off
	global_load_dwordx4 v[40:43], v[86:87], off
	v_addc_co_u32_e32 v97, vcc, 0, v93, vcc
	global_load_dwordx4 v[52:55], v[92:93], off
	global_load_dwordx4 v[56:59], v[96:97], off
	s_branch .LBB0_463
.Lbl_even:
	s_cmp_le_i32 s62, s63
	s_cbranch_scc1 .Lbl_even_w4
	s_waitcnt vmcnt(0)
	s_branch .Lbl_even_go

; template <int MODE, int NKB> ...
;     ...
;     for (int i = 0; i < NKB; ++i) { const LAS bf16_t* kp = Ks + (kb0 + 16 * i + l15) * KST + 8 * quad;
; #pragma unroll
;         for (int s = 0; s < NS; ++s) st[s][i] = (f32x4){negm, negm, negm, negm};
; #pragma unroll
;         for (int kc = 0; kc < 2; ++kc) {
;             if (MODE == 2) {
; #pragma unroll
;                 for (int s = 0; s < NS; ++s) { const bf16x8 a = *(const LAS bf16x8*)(kp + 64 * s + 32 * kc); st[s][i] = __builtin_amdgcn_mfma_f32_16x16x32_bf16(a, qf[s][kc], st[s][i], 0, 0, 0); }
;                 if (kc == 1 && (i & 1)) __builtin_amdgcn_sched_barrier(0);
;             } else { const bf16x8 a = *(const LAS bf16x8*)(kp + 32 * kc);
; #pragma unroll
;                 for (int s = 0; s < NS; ++s) st[s][i] = __builtin_amdgcn_mfma_f32_16x16x32_bf16(a, qf[s][kc], st[s][i], 0, 0, 0); } } }
;     if (MODE == 2) __builtin_amdgcn_sched_barrier(0);
;     if (masked) {
;         if (MODE == 0) {
; #pragma unroll
;             for (int i = 0; i < NKB; ++i)
; #pragma unroll
;                 for (int r = 0; r < 4; ++r) { const int d = mp - (kb0 + 16 * i + 4 * quad + r); const bool bad = (d > 128) || (d < -128);
; #pragma unroll
;                     for (int s = 0; s < NS; ++s) st[s][i][r] = bad ? NEGBIG : st[s][i][r]; }
;         }
;         if (MODE == 1) {
; #pragma unroll
;             for (int i = 0; i < NKB; ++i)
; #pragma unroll
;                 for (int r = 0; r < 4; ++r) { const int key = kb0 + 16 * i + 4 * quad + r; const bool valid = (key >= mp) && (key < mp + 16);
;                     const float bias = valid ? brow[key] : 0.f; st[0][i][r] = valid ? st[0][i][r] + bias : NEGBIG; }
;         }
;     }
;     bf16x8 pf[NS][NKB / 2];
; #pragma unroll
;     for (int s = 0; s < NS; ++s) {
;         if (MODE == 2) __builtin_amdgcn_sched_barrier(0);
;         float ps = 0.f;
; #pragma unroll
; template <int MODE>
; DI void attn_unit(const Ctx& C, const bf16_t* __restrict__ Z, bf16_t* __restrict__ Y, int b, int qsel, int hsel, bool ctxq,
;                   const float* sinkp, const float* rpb_h, float lam, float post_scale, const float* subln, const float mref) {
;     ...
;     for (int t = 0; t < nt; ++t) {
;         if (t + 1 < nt) {
;             if ((t + 1) & 1) { WRITE(1, kB, vB); if (t + 3 < nt) ISSUE(t + 3, kB, vB); }
;             else { WRITE(0, kA, vA); if (t + 3 < nt) ISSUE(t + 3, kA, vA); }
.Lbl_even_go:
	ds_write_b128 v117, v[44:47] offset:36864
	ds_write_b128 v117, v[48:51] offset:46080
	ds_write_b16 v107, v60 offset:55296
	ds_write_b16_d16_hi v107, v60 offset:55568
	ds_write_b16 v107, v61 offset:55840
	ds_write_b16_d16_hi v107, v61 offset:56112
	ds_write_b16 v107, v62 offset:56384
	ds_write_b16_d16_hi v107, v62 offset:56656
	ds_write_b16 v107, v63 offset:56928
	ds_write_b16_d16_hi v107, v63 offset:57200
	ds_write_b16 v107, v64 offset:55424
	ds_write_b16_d16_hi v107, v64 offset:55696
	ds_write_b16 v107, v65 offset:55968
	ds_write_b16_d16_hi v107, v65 offset:56240
	ds_write_b16 v107, v66 offset:56512
	ds_write_b16_d16_hi v107, v66 offset:56784
	ds_write_b16 v107, v67 offset:57056
	ds_write_b16_d16_hi v107, v67 offset:57328
	s_cmp_ge_i32 s62, s63
	s_cbranch_scc1 .LBB0_463
	s_mul_i32 s26, s66, 0x2200
	s_mul_hi_i32 s27, s66, 0x2200
	s_add_u32 s26, s8, s26
	s_addc_u32 s27, s9, s27
	v_lshl_add_u64 v[84:85], v[0:1], 1, s[26:27]
	v_add_co_u32_e32 v86, vcc, 0x88000, v84
	v_lshl_add_u64 v[92:93], v[102:103], 1, s[26:27]
	s_nop 0
	v_addc_co_u32_e32 v87, vcc, 0, v85, vcc
	v_add_co_u32_e32 v96, vcc, 0x88000, v92
	global_load_dwordx4 v[44:47], v[84:85], off
	global_load_dwordx4 v[48:51], v[86:87], off
	v_addc_co_u32_e32 v97, vcc, 0, v93, vcc
	global_load_dwordx4 v[60:63], v[92:93], off
	global_load_dwordx4 v[64:67], v[96:97], off
.LBB0_463:
	s_bitcmp1_b32 s70, 0
	s_cselect_b32 s26, 0x9000, 0
	s_add_i32 s69, s26, 0
	s_cmp_gt_u32 s70, 1
	s_cselect_b64 s[26:27], -1, 0
	s_mov_b64 s[28:29], -1
	s_and_b64 vcc, exec, s[26:27]
	s_cbranch_vccz .LBB0_483
	s_cmp_ge_i32 s61, s36
	s_cselect_b64 s[28:29], -1, 0
	s_min_i32 s70, s60, s65
	s_cmp_gt_i32 s70, s61
	s_cselect_b64 s[70:71], -1, 0
	s_and_b64 s[28:29], s[70:71], s[28:29]
	s_andn2_b64 vcc, exec, s[28:29]
	v_mov_b32_e32 v99, v83
	v_mov_b32_e32 v98, v82
	v_mov_b32_e32 v97, v81
	v_mov_b32_e32 v96, v80
	v_mov_b32_e32 v95, v79
	v_mov_b32_e32 v94, v78
	v_mov_b32_e32 v93, v77
	v_mov_b32_e32 v92, v76
	v_mov_b32_e32 v91, v75
	v_mov_b32_e32 v90, v74
	v_mov_b32_e32 v89, v73
	v_mov_b32_e32 v88, v72
	v_mov_b32_e32 v87, v71
	v_mov_b32_e32 v86, v70
	v_mov_b32_e32 v85, v69
	v_mov_b32_e32 v84, v68
	v_mov_b32_e32 v125, v119
	s_cbranch_vccnz .LBB0_482
	v_add3_u32 v92, s69, v133, v110
	ds_read_b128 v[84:87], v92
	ds_read_b128 v[88:91], v92 offset:64
	s_waitcnt lgkmcnt(1)
	v_mfma_f32_16x16x32_bf16 v[84:87], v[84:87], v[28:31], v[24:27]
	s_waitcnt lgkmcnt(0)
	v_mfma_f32_16x16x32_bf16 v[88:91], v[88:91], v[32:35], v[84:87]
	s_nop 5
	ds_read_b128 v[84:87], v92 offset:2304
	ds_read_b128 v[92:95], v92 offset:2368
	s_waitcnt lgkmcnt(1)
	v_mfma_f32_16x16x32_bf16 v[84:87], v[84:87], v[28:31], v[24:27]
	s_waitcnt lgkmcnt(0)
	v_mfma_f32_16x16x32_bf16 v[84:87], v[92:95], v[32:35], v[84:87]
	v_add_u32_e32 v124, s68, v118
	v_add_u32_e32 v124, 0x121b0, v124
	ds_read2_b32 v[96:97], v124 offset1:1
	ds_read2_b32 v[98:99], v124 offset0:2 offset1:3
	ds_read2_b32 v[126:127], v124 offset0:16 offset1:17
	ds_read2_b32 v[128:129], v124 offset0:18 offset1:19
	s_waitcnt lgkmcnt(0)
	v_add_f32_e32 v96, v88, v96
	v_add_f32_e32 v97, v89, v97
	v_add_f32_e32 v98, v90, v98
	v_add_f32_e32 v99, v91, v99
	v_add_f32_e32 v126, v84, v126
	v_add_f32_e32 v127, v85, v127
	v_add_f32_e32 v128, v86, v128
	v_add_f32_e32 v129, v87, v129
	v_cndmask_b32_e64 v93, v231, v96, s[6:7]
	v_cndmask_b32_e64 v92, v231, v97, s[14:15]
	v_cndmask_b32_e64 v89, v231, v98, s[16:17]
	v_cndmask_b32_e64 v88, v231, v99, s[18:19]
	v_cndmask_b32_e64 v91, v231, v126, s[20:21]
	v_cndmask_b32_e64 v90, v231, v127, s[22:23]
	v_cndmask_b32_e64 v85, v231, v128, s[24:25]
	v_cndmask_b32_e64 v84, v231, v129, s[4:5]
	v_exp_f32_e32 v86, v93
	v_exp_f32_e32 v92, v92
	v_exp_f32_e32 v89, v89
	v_exp_f32_e32 v88, v88
	v_add_f32_e32 v87, 0, v86
	v_exp_f32_e32 v91, v91
	v_add_f32_e32 v87, v87, v92
	v_exp_f32_e32 v90, v90
	v_add_f32_e32 v87, v87, v89
	v_exp_f32_e32 v85, v85
	v_add_f32_e32 v87, v87, v88
	v_exp_f32_e32 v84, v84
	v_add_f32_e32 v87, v87, v91
	s_lshl_b32 s28, s47, 1
	v_add_f32_e32 v87, v87, v90
	s_add_i32 s28, s69, s28
	v_add_f32_e32 v87, v87, v85
	v_add3_u32 v124, s28, v120, v111
	v_add_f32_e32 v87, v87, v84
	v_cvt_pk_bf16_f32 v96, v86, v92
	v_cvt_pk_bf16_f32 v97, v89, v88
	v_cvt_pk_bf16_f32 v99, v85, v84
	v_add_u32_e32 v84, 0x4800, v124
	v_add_u32_e32 v88, 0x5800, v124
	v_add_u32_e32 v92, 0x6800, v124
	v_add_u32_e32 v124, 0x7800, v124
	v_add_f32_e32 v125, v119, v87
	v_cvt_pk_bf16_f32 v98, v91, v90
	ds_read2_b64 v[84:87], v84 offset1:4
	ds_read2_b64 v[88:91], v88 offset0:32 offset1:36
	ds_read2_b64 v[92:95], v92 offset0:64 offset1:68
	ds_read2_b64 v[126:129], v124 offset0:96 offset1:100
	s_waitcnt lgkmcnt(3)
	v_mfma_f32_16x16x32_bf16 v[84:87], v[84:87], v[96:99], v[68:71]
	s_waitcnt lgkmcnt(2)
	v_mfma_f32_16x16x32_bf16 v[88:91], v[88:91], v[96:99], v[72:75]
	s_waitcnt lgkmcnt(1)
	v_mfma_f32_16x16x32_bf16 v[92:95], v[92:95], v[96:99], v[76:79]
	s_waitcnt lgkmcnt(0)
	v_mfma_f32_16x16x32_bf16 v[96:99], v[126:129], v[96:99], v[80:83]

; template <int MODE, int NKB> ...
;     ...
;     for (int i = 0; i < NKB; ++i) { const LAS bf16_t* kp = Ks + (kb0 + 16 * i + l15) * KST + 8 * quad;
; #pragma unroll
;         for (int s = 0; s < NS; ++s) st[s][i] = (f32x4){negm, negm, negm, negm};
; #pragma unroll
;         for (int kc = 0; kc < 2; ++kc) {
;             if (MODE == 2) {
; #pragma unroll
;                 for (int s = 0; s < NS; ++s) { const bf16x8 a = *(const LAS bf16x8*)(kp + 64 * s + 32 * kc); st[s][i] = __builtin_amdgcn_mfma_f32_16x16x32_bf16(a, qf[s][kc], st[s][i], 0, 0, 0); }
;                 if (kc == 1 && (i & 1)) __builtin_amdgcn_sched_barrier(0);
;             } else { const bf16x8 a = *(const LAS bf16x8*)(kp + 32 * kc);
; #pragma unroll
;                 for (int s = 0; s < NS; ++s) st[s][i] = __builtin_amdgcn_mfma_f32_16x16x32_bf16(a, qf[s][kc], st[s][i], 0, 0, 0); } } }
;     if (MODE == 2) __builtin_amdgcn_sched_barrier(0);
;     if (masked) {
;         if (MODE == 0) {
; #pragma unroll
;             for (int i = 0; i < NKB; ++i)
; #pragma unroll
;                 for (int r = 0; r < 4; ++r) { const int d = mp - (kb0 + 16 * i + 4 * quad + r); const bool bad = (d > 128) || (d < -128);
; #pragma unroll
;                     for (int s = 0; s < NS; ++s) st[s][i][r] = bad ? NEGBIG : st[s][i][r]; }
;         }
;         if (MODE == 1) {
; #pragma unroll
;             for (int i = 0; i < NKB; ++i)
; #pragma unroll
;                 for (int r = 0; r < 4; ++r) { const int key = kb0 + 16 * i + 4 * quad + r; const bool valid = (key >= mp) && (key < mp + 16);
;                     const float bias = valid ? brow[key] : 0.f; st[0][i][r] = valid ? st[0][i][r] + bias : NEGBIG; }
;         }
;     }
;     bf16x8 pf[NS][NKB / 2];
; #pragma unroll
;     for (int s = 0; s < NS; ++s) {
;         if (MODE == 2) __builtin_amdgcn_sched_barrier(0);
;         float ps = 0.f;
; #pragma unroll
;         for (int i = 0; i < NKB; ++i)
; #pragma unroll
;             for (int r = 0; r < 4; ++r) { const float p = fast_exp2(st[s][i][r]); st[s][i][r] = p; ps += p; }
;         lsum[s] += ps;
; #pragma unroll
;         for (int c = 0; c < NKB / 2; ++c) { u32x4 pw; pw.x = pk2(st[s][2 * c][0], st[s][2 * c][1]); pw.y = pk2(st[s][2 * c][2], st[s][2 * c][3]); pw.z = pk2(st[s][2 * c + 1][0], st[s][2 * c + 1][1]); pw.w = pk2(st[s][2 * c + 1][2], st[s][2 * c + 1][3]);
;             pf[s][c] = __builtin_bit_cast(bf16x8, pw); }
.LBB0_485:
	s_andn2_b64 vcc, exec, s[26:27]
	s_mov_b64 s[26:27], -1
	s_cbranch_vccnz .LBB0_505
	s_add_i32 s28, s61, 1
	s_cmp_ge_i32 s28, s36
	s_cselect_b64 s[26:27], -1, 0
	s_min_i32 s29, s60, s65
	s_cmp_gt_i32 s29, s28
	s_cselect_b64 s[28:29], -1, 0
	s_and_b64 s[26:27], s[28:29], s[26:27]
	s_andn2_b64 vcc, exec, s[26:27]
	v_mov_b32_e32 v83, v99
	v_mov_b32_e32 v82, v98
	v_mov_b32_e32 v81, v97
	v_mov_b32_e32 v80, v96
	v_mov_b32_e32 v79, v95
	v_mov_b32_e32 v78, v94
	v_mov_b32_e32 v77, v93
	v_mov_b32_e32 v76, v92
	v_mov_b32_e32 v75, v91
	v_mov_b32_e32 v74, v90
	v_mov_b32_e32 v73, v89
	v_mov_b32_e32 v72, v88
	v_mov_b32_e32 v71, v87
	v_mov_b32_e32 v70, v86
	v_mov_b32_e32 v69, v85
	v_mov_b32_e32 v68, v84
	v_mov_b32_e32 v119, v125
	s_cbranch_vccnz .LBB0_504
	v_add3_u32 v76, s69, v133, v110
	ds_read_b128 v[68:71], v76 offset:9216
	ds_read_b128 v[72:75], v76 offset:9280
	s_waitcnt lgkmcnt(1)
	v_mfma_f32_16x16x32_bf16 v[68:71], v[68:71], v[28:31], v[24:27]
	s_waitcnt lgkmcnt(0)
	v_mfma_f32_16x16x32_bf16 v[72:75], v[72:75], v[32:35], v[68:71]
	s_nop 5
	ds_read_b128 v[68:71], v76 offset:11520
	ds_read_b128 v[76:79], v76 offset:11584
	s_waitcnt lgkmcnt(1)
	v_mfma_f32_16x16x32_bf16 v[68:71], v[68:71], v[28:31], v[24:27]
	s_waitcnt lgkmcnt(0)
	v_mfma_f32_16x16x32_bf16 v[68:71], v[76:79], v[32:35], v[68:71]
	v_add_u32_e32 v78, s68, v118
	v_add_u32_e32 v78, 0x1222c, v78
	ds_read2_b32 v[80:81], v78 offset1:1
	ds_read2_b32 v[82:83], v78 offset0:2 offset1:3
	ds_read2_b32 v[128:129], v78 offset0:16 offset1:17
	ds_read2_b32 v[130:131], v78 offset0:18 offset1:19
	s_waitcnt lgkmcnt(0)
	v_add_f32_e32 v80, v72, v80
	v_add_f32_e32 v81, v73, v81
	v_add_f32_e32 v82, v74, v82
	v_add_f32_e32 v83, v75, v83
	v_add_f32_e32 v128, v68, v128
	v_add_f32_e32 v129, v69, v129
	v_add_f32_e32 v130, v70, v130
	v_add_f32_e32 v131, v71, v131
	v_cndmask_b32_e64 v77, v231, v80, s[6:7]
	v_cndmask_b32_e64 v76, v231, v81, s[14:15]
	v_cndmask_b32_e64 v73, v231, v82, s[16:17]
	v_cndmask_b32_e64 v72, v231, v83, s[18:19]
	v_cndmask_b32_e64 v75, v231, v128, s[20:21]
	v_cndmask_b32_e64 v74, v231, v129, s[22:23]
	v_cndmask_b32_e64 v69, v231, v130, s[24:25]
	v_cndmask_b32_e64 v68, v231, v131, s[4:5]
	v_exp_f32_e32 v70, v77
	v_exp_f32_e32 v76, v76
	v_exp_f32_e32 v73, v73
	v_exp_f32_e32 v72, v72
	v_add_f32_e32 v71, 0, v70
	v_exp_f32_e32 v75, v75
	v_add_f32_e32 v71, v71, v76
	v_exp_f32_e32 v74, v74
	v_add_f32_e32 v71, v71, v73
	v_exp_f32_e32 v69, v69
	v_add_f32_e32 v71, v71, v72
	v_exp_f32_e32 v68, v68
	v_add_f32_e32 v71, v71, v75
	s_lshl_b32 s26, s47, 1
	v_add_f32_e32 v71, v71, v74
	s_add_i32 s69, s69, s26
	v_add_f32_e32 v71, v71, v69
	v_add3_u32 v127, s69, v120, v111
	v_add_f32_e32 v71, v71, v68
	v_cvt_pk_bf16_f32 v80, v70, v76
	v_cvt_pk_bf16_f32 v81, v73, v72
	v_cvt_pk_bf16_f32 v83, v69, v68
	v_add_u32_e32 v68, 0x4800, v127
	v_add_u32_e32 v72, 0x5800, v127
	v_add_u32_e32 v76, 0x6800, v127
	v_add_u32_e32 v127, 0x7800, v127
	v_add_f32_e32 v119, v125, v71
	v_cvt_pk_bf16_f32 v82, v75, v74
	ds_read2_b64 v[68:71], v68 offset0:16 offset1:20
	ds_read2_b64 v[72:75], v72 offset0:48 offset1:52
	ds_read2_b64 v[76:79], v76 offset0:80 offset1:84
	ds_read2_b64 v[128:131], v127 offset0:112 offset1:116
	s_waitcnt lgkmcnt(3)
	v_mfma_f32_16x16x32_bf16 v[68:71], v[68:71], v[80:83], v[84:87]
	s_waitcnt lgkmcnt(2)
	v_mfma_f32_16x16x32_bf16 v[72:75], v[72:75], v[80:83], v[88:91]
	s_waitcnt lgkmcnt(1)
	v_mfma_f32_16x16x32_bf16 v[76:79], v[76:79], v[80:83], v[92:95]
	s_waitcnt lgkmcnt(0)
	v_mfma_f32_16x16x32_bf16 v[80:83], v[128:131], v[80:83], v[96:99]
